# p3a S2: 64-lane cumulative log-decay by the DPP scan idiom (row_shr 1,2,4,8 + row_bcast 15,31) instead of six ds_bpermute round trips
# speedup vs baseline: 1.0039x; 1.0015x over previous
.LBB0_614:
	s_or_b64 exec, exec, s[10:11]
	s_add_u32 s8, s58, s8
	s_addc_u32 s9, s59, s9
	v_mov_b32_e32 v4, v243
	v_mul_f32_e32 v2, 0xbfb8aa3b, v2
	v_exp_f32_e32 v2, v2
	v_mul_f32_e32 v4, 0x3fb8aa3b, v4
	v_exp_f32_e32 v4, v4
	v_add_f32_e32 v2, 1.0, v2
	v_rcp_f32_e32 v2, v2
	v_mul_f32_e64 v4, v3, -v4
	s_nop 1
	v_add_f32_dpp v4, v4, v4 row_shr:1 row_mask:0xf bank_mask:0xf bound_ctrl:1
	s_nop 1
	v_add_f32_dpp v4, v4, v4 row_shr:2 row_mask:0xf bank_mask:0xf bound_ctrl:1
	s_nop 1
	v_add_f32_dpp v4, v4, v4 row_shr:4 row_mask:0xf bank_mask:0xf bound_ctrl:1
	s_nop 1
	v_add_f32_dpp v4, v4, v4 row_shr:8 row_mask:0xf bank_mask:0xf bound_ctrl:1
	s_nop 1
	v_add_f32_dpp v4, v4, v4 row_bcast:15 row_mask:0xa bank_mask:0xf
	s_nop 1
	v_add_f32_dpp v4, v4, v4 row_bcast:31 row_mask:0xc bank_mask:0xf
	s_lshl_b32 s4, s64, 7
	v_readlane_b32 s5, v249, 4
	s_or_b32 s4, s4, s5
	v_add_u32_e32 v3, s4, v160
	s_add_i32 s4, s40, s72
	s_lshr_b32 s5, s4, 4
	s_cmp_eq_u32 s5, 2
	s_cselect_b32 s6, s17, 0x26000000
	s_cmp_lg_u32 s5, 1
	s_cselect_b32 s5, s6, 0x1d000000
	s_cmp_gt_u32 s4, 15
	ds_bpermute_b32 v5, v192, v4
	s_cselect_b32 s4, s5, 0x1ed00000
	s_add_u32 s4, s70, s4
	v_lshl_add_u32 v3, v3, 2, 0
	s_addc_u32 s5, s71, 0
	s_lshl_b32 s6, s40, 6
	v_add_u32_e32 v6, 0x20800, v3
	s_and_b32 s6, s6, 0x3c0
	ds_write_b32 v6, v2
	v_add_u32_e32 v2, 0x21000, v3
	s_add_i32 s6, s6, s85
	ds_write_b32 v2, v4
	s_mul_hi_i32 s7, s6, 0x7400
	s_mulk_i32 s6, 0x7400
	v_mul_f32_e32 v2, 0x3fb8aa3b, v4
	s_waitcnt lgkmcnt(2)
	v_sub_f32_e32 v4, v5, v4
	s_add_u32 s4, s4, s6
	v_mul_f32_e32 v4, 0x3fb8aa3b, v4
	s_addc_u32 s5, s5, s7
	v_exp_f32_e32 v6, v2
	v_exp_f32_e32 v4, v4
	v_lshl_add_u64 v[2:3], v[160:161], 2, s[4:5]
	v_add_co_u32_e32 v2, vcc, 0x7000, v2
	s_nop 1
	v_addc_co_u32_e32 v3, vcc, 0, v3, vcc
	global_store_dword v[2:3], v6, off sc1
	global_store_dword v[2:3], v4, off offset:256 sc1
